# DA late waves run QK(t) before P.V(t-1) (packed P kept in a save area) so both waves of a SIMD start a step with the short MFMA chain
# baseline (speedup 1.0000x reference)
; template <int MODE>
; DI void attn_unit(LAS unsigned char* lds, const bf16_t* Qg, int ldq, const bf16_t* Kg, int ldk, const bf16_t* VTg, int ldvt, bf16_t* Og, int ldo,
;                   int q0, int NT, const float* gout, const float* relb, float lam, float osc, const float* qgain) {
;     ...
;     AT_GLOAD(AT_KEY0(0)); AT_LSTORE(0, 0);
;     __syncthreads();
;     float mhat = 0.f, lrun = 0.f, R = 0.f;
;     f32x16 negm;
; #pragma unroll
;     for (int i = 0; i < 16; ++i) negm[i] = c15;
;     f32x16 o[NDB];
; #pragma unroll
;     for (int d = 0; d < NDB; ++d)
; #pragma unroll
;         for (int i = 0; i < 16; ++i) o[d][i] = 0.f;
;     const bool skew = (MODE != 2) && (wid >= 4);
;     u32x4 pk[4];
; #pragma unroll
;     for (int j = 0; j < 4; ++j) pk[j] = (u32x4){0u, 0u, 0u, 0u};
.LBB0_179:
	s_or_b64 exec, exec, s[10:11]
	v_add_f32_e32 v157, v161, v157
	v_pk_add_f32 v[156:157], v[156:157], v[0:1]
	v_add_f32_e32 v155, v155, v153
	v_pk_add_f32 v[156:157], v[156:157], v[156:157] op_sel_hi:[0,1]
	v_mov_b32_e32 v153, v157
	v_pk_add_f32 v[152:153], v[154:155], v[152:153]
	v_add_f32_e32 v115, v115, v113
	v_pk_add_f32 v[152:153], v[152:153], v[152:153] op_sel_hi:[0,1]
	v_mov_b32_e32 v113, v153
	v_pk_add_f32 v[112:113], v[114:115], v[112:113]
	v_add_f32_e32 v111, v111, v109
	v_pk_add_f32 v[112:113], v[112:113], v[112:113] op_sel_hi:[0,1]
	v_mov_b32_e32 v109, v113
	v_pk_add_f32 v[108:109], v[110:111], v[108:109]
	v_add_f32_e32 v107, v160, v81
	v_pk_add_f32 v[108:109], v[108:109], v[108:109] op_sel_hi:[0,1]
	v_mov_b32_e32 v105, v109
	v_pk_add_f32 v[104:105], v[106:107], v[104:105]
	v_add_f32_e32 v81, v79, v77
	v_pk_add_f32 v[104:105], v[104:105], v[104:105] op_sel_hi:[0,1]
	v_mov_b32_e32 v79, v105
	v_pk_add_f32 v[78:79], v[80:81], v[78:79]
	v_add_f32_e32 v77, v75, v73
	v_pk_add_f32 v[78:79], v[78:79], v[78:79] op_sel_hi:[0,1]
	v_mov_b32_e32 v75, v79
	v_pk_add_f32 v[74:75], v[76:77], v[74:75]
	s_mov_b32 s2, 0xcc00
	v_pk_add_f32 v[74:75], v[74:75], v[74:75] op_sel_hi:[0,1]
	v_add_f32_e32 v73, v71, v69
	v_mov_b32_e32 v71, v75
	v_add3_u32 v0, v185, v186, s2
	v_pk_add_f32 v[70:71], v[72:73], v[70:71]
	s_waitcnt vmcnt(0)
	ds_write2_b64 v0, v[140:141], v[142:143] offset1:1
	v_add3_u32 v0, v185, v187, s2
	v_pk_add_f32 v[70:71], v[70:71], v[70:71] op_sel_hi:[0,1]
	ds_write2_b64 v0, v[144:145], v[146:147] offset1:1
	v_add_u32_e32 v0, v82, v83
	v_ashrrev_i32_e32 v70, 4, v0
	v_and_b32_e32 v0, -16, v0
	v_mov_b32_e32 v69, v71
	v_sub_u32_e32 v0, v82, v0
	v_pk_add_f32 v[152:153], v[68:69], 0 op_sel_hi:[1,0]
	v_lshlrev_b32_e32 v72, 3, v0
	v_lshlrev_b32_e32 v193, 4, v0
	v_add_u32_e32 v0, s21, v150
	v_lshlrev_b32_e32 v69, 2, v159
	s_lshl_b32 s12, s29, 1
	s_lshr_b32 s19, s24, 6
	v_sub_u32_e32 v0, v0, v69
	s_lshl_b32 s2, s27, 7
	s_add_i32 s14, s12, 2
	s_add_i32 s18, s19, 1
	s_addk_i32 s24, 0xff41
	v_subrev_u32_e32 v0, s2, v0
	s_lshl_b32 s25, s29, 9
	s_lshl_b64 s[2:3], s[16:17], 12
	s_add_u32 s2, s20, s2
	s_addc_u32 s3, 0, s3
	v_subrev_u32_e32 v0, s25, v0
	s_add_u32 s2, s2, 0x18000100
	v_add_u32_e32 v194, 0, v0
	s_addc_u32 s3, s3, 0
	v_and_b32_e32 v0, 7, v82
	v_lshl_add_u64 v[76:77], s[2:3], 0, v[100:101]
	v_lshlrev_b32_e32 v0, 4, v0
	v_lshl_add_u64 v[154:155], v[76:77], 0, v[0:1]
	v_lshl_add_u64 v[76:77], s[2:3], 0, v[102:103]
	s_add_u32 s2, s8, s28
	s_addc_u32 s3, s9, 0
	v_mul_u32_u24_e32 v191, 0x88, v159
	v_ashrrev_i32_e32 v159, 31, v158
	s_add_u32 s2, s2, 0x8080400
	v_ashrrev_i32_e32 v71, 31, v70
	v_lshlrev_b32_e32 v74, 3, v162
	v_mul_lo_u32 v192, v70, s56
	v_lshl_add_u64 v[156:157], v[76:77], 0, v[0:1]
	v_lshlrev_b64 v[76:77], 12, v[158:159]
	s_addc_u32 s3, s3, 0
	v_lshlrev_b64 v[70:71], 12, v[70:71]
	v_sub_f32_e32 v68, v66, v152
	v_ashrrev_i32_e32 v73, 31, v72
	v_ashrrev_i32_e32 v75, 31, v74
	v_lshl_add_u64 v[76:77], s[2:3], 0, v[76:77]
	v_lshl_add_u64 v[70:71], s[2:3], 0, v[70:71]
	s_mov_b32 s13, 1
	s_mov_b32 s15, 2
	s_mov_b32 s21, s29
	v_lshl_add_u64 v[158:159], v[74:75], 1, v[76:77]
	v_lshl_add_u64 v[160:161], v[72:73], 1, v[70:71]
	s_movk_i32 s28, 0xff00
	s_mov_b32 s29, 64
	v_mov_b32_e32 v69, v68
	v_mov_b32_e32 v70, v68
	v_mov_b32_e32 v71, v68
	v_mov_b32_e32 v72, v68
	v_mov_b32_e32 v73, v68
	v_mov_b32_e32 v74, v68
	v_mov_b32_e32 v75, v68
	v_mov_b32_e32 v76, v68
	v_mov_b32_e32 v77, v68
	v_mov_b32_e32 v78, v68
	v_mov_b32_e32 v79, v68
	v_mov_b32_e32 v80, v68
	v_mov_b32_e32 v81, v68
	v_mov_b32_e32 v82, v68
	v_mov_b32_e32 v83, v68
	v_readlane_b32 s2, v253, 40
	v_readlane_b32 s3, v253, 41
	s_nop 1
	v_lshl_add_u64 v[154:155], s[2:3], 0, v[154:155]
	v_lshl_add_u64 v[156:157], s[2:3], 0, v[156:157]
	v_lshl_add_u64 v[158:159], s[2:3], 0, v[158:159]
	v_lshl_add_u64 v[160:161], s[2:3], 0, v[160:161]
	v_mov_b64_e32 v[172:173], v[96:97]
	v_mov_b64_e32 v[174:175], v[98:99]
	v_mov_b64_e32 v[176:177], v[92:93]
	v_mov_b64_e32 v[178:179], v[94:95]
	v_mov_b64_e32 v[220:221], v[88:89]
	v_mov_b64_e32 v[222:223], v[90:91]
	v_mov_b64_e32 v[224:225], v[84:85]
	v_mov_b64_e32 v[226:227], v[86:87]
	s_waitcnt lgkmcnt(0)
	s_barrier
	s_branch .LBB0_182

; #define LAS __attribute__((address_space(3)))
; #define MFMA32(a, b, c) __builtin_amdgcn_mfma_f32_32x32x16_bf16((a), (b), (c), 0, 0, 0)
; template <int MODE>
; DI void attn_unit(LAS unsigned char* lds, const bf16_t* Qg, int ldq, const bf16_t* Kg, int ldk, const bf16_t* VTg, int ldvt, bf16_t* Og, int ldo,
;                   int q0, int NT, const float* gout, const float* relb, float lam, float osc, const float* qgain) {
;     ...
;         if (MODE == 2) active = (NT - 1 - t) <= TD; else active = t < ntw;
;         bool alive = true;
;         if (MODE == 2) alive = !active || __any(R > -150.f);
;         if (skew && t >= 1 && (t - 1) < ntw) pvdo(vprev, pk);
;         if (active && alive) {
;             const LAS unsigned char* Kb = lds + (cur ? KB1 : KB0) + r32 * KSTR + mm * 128 + hi * 16;
;             f32x16 p0, p1;
; #pragma unroll
;             for (int s = 0; s < NS; ++s) { const bf16x8 a0 = *(const LAS bf16x8*)(Kb + s * 32), a1 = *(const LAS bf16x8*)(Kb + 32 * KSTR + s * 32);
;                 if (s == 0) { p0 = MFMA32(a0, qf[0], negm); p1 = MFMA32(a1, qf[0], negm); } else { p0 = MFMA32(a0, qf[s], p0); p1 = MFMA32(a1, qf[s], p1); } }
.LBB0_188:
	s_add_i32 s2, s15, -1
	s_cmp_le_u32 s2, s18
	s_cselect_b64 vcc, -1, 0
	s_and_b64 vcc, s[0:1], vcc
.LBB0_190:
	s_cmp_gt_u32 s2, s19
	s_cbranch_scc1 .Lda_inactive
	s_and_b32 s10, s2, 1
	s_cmp_eq_u32 s10, 0
	s_cselect_b32 s2, 0, 0x4400
	v_add_u32_e32 v0, s2, v188
	ds_read_b128 v[196:199], v0
	ds_read_b128 v[200:203], v0 offset:8704
	ds_read_b128 v[204:207], v0 offset:32
	ds_read_b128 v[208:211], v0 offset:8736
	ds_read_b128 v[212:215], v0 offset:64
	ds_read_b128 v[216:219], v0 offset:8768
	s_waitcnt lgkmcnt(4)
	v_mfma_f32_32x32x16_bf16 v[84:99], v[196:199], v[116:119], v[68:83]
	v_mfma_f32_32x32x16_bf16 v[100:115], v[200:203], v[116:119], v[68:83]
	ds_read_b128 v[196:199], v0 offset:96
	ds_read_b128 v[200:203], v0 offset:8800
	s_waitcnt lgkmcnt(4)
	v_mfma_f32_32x32x16_bf16 v[84:99], v[204:207], v[120:123], v[84:99]
	v_mfma_f32_32x32x16_bf16 v[100:115], v[208:211], v[120:123], v[100:115]
	s_waitcnt lgkmcnt(2)
	v_mfma_f32_32x32x16_bf16 v[84:99], v[212:215], v[124:127], v[84:99]
	v_mfma_f32_32x32x16_bf16 v[100:115], v[216:219], v[124:127], v[100:115]
	s_waitcnt lgkmcnt(0)
	v_mfma_f32_32x32x16_bf16 v[84:99], v[196:199], v[128:131], v[84:99]
	v_mfma_f32_32x32x16_bf16 v[100:115], v[200:203], v[128:131], v[100:115]
	s_cbranch_vccz .Lda_nopv
	s_mul_i32 s3, s13, 0x4400
	s_addk_i32 s3, 0xbc00
	s_cmp_lg_u32 s13, 0
	s_cselect_b32 s3, s3, 0x8800
	v_add_u32_e32 v0, s3, v67
	v_add_u32_e32 v236, 0x8800, v0
	v_add_u32_e32 v237, 0x9800, v0
	v_add_u32_e32 v238, 0xa800, v0
	v_add_u32_e32 v239, 0xb800, v0
	ds_read2_b64 v[196:199], v236 offset1:2
	ds_read2_b64 v[200:203], v236 offset0:4 offset1:6
	ds_read2_b64 v[204:207], v236 offset0:8 offset1:10
	ds_read2_b64 v[208:211], v236 offset0:12 offset1:14
	s_waitcnt lgkmcnt(2)
	v_mfma_f32_32x32x16_bf16 v[50:65], v[196:199], v[172:175], v[50:65]
	v_mfma_f32_32x32x16_bf16 v[50:65], v[200:203], v[176:179], v[50:65]
	ds_read2_b64 v[196:199], v237 offset0:32 offset1:34
	ds_read2_b64 v[200:203], v237 offset0:36 offset1:38
	s_waitcnt lgkmcnt(2)
	v_mfma_f32_32x32x16_bf16 v[50:65], v[204:207], v[220:223], v[50:65]
	v_mfma_f32_32x32x16_bf16 v[50:65], v[208:211], v[224:227], v[50:65]
	ds_read2_b64 v[204:207], v237 offset0:40 offset1:42
	ds_read2_b64 v[208:211], v237 offset0:44 offset1:46
	s_waitcnt lgkmcnt(2)
	v_mfma_f32_32x32x16_bf16 v[34:49], v[196:199], v[172:175], v[34:49]
	v_mfma_f32_32x32x16_bf16 v[34:49], v[200:203], v[176:179], v[34:49]
	ds_read2_b64 v[196:199], v238 offset0:64 offset1:66
	ds_read2_b64 v[200:203], v238 offset0:68 offset1:70
	s_waitcnt lgkmcnt(2)
	v_mfma_f32_32x32x16_bf16 v[34:49], v[204:207], v[220:223], v[34:49]
	v_mfma_f32_32x32x16_bf16 v[34:49], v[208:211], v[224:227], v[34:49]
	ds_read2_b64 v[204:207], v238 offset0:72 offset1:74
	ds_read2_b64 v[208:211], v238 offset0:76 offset1:78
	s_waitcnt lgkmcnt(2)
	v_mfma_f32_32x32x16_bf16 v[18:33], v[196:199], v[172:175], v[18:33]
	v_mfma_f32_32x32x16_bf16 v[18:33], v[200:203], v[176:179], v[18:33]
	ds_read2_b64 v[196:199], v239 offset0:96 offset1:98
	ds_read2_b64 v[200:203], v239 offset0:100 offset1:102
	s_waitcnt lgkmcnt(2)
	v_mfma_f32_32x32x16_bf16 v[18:33], v[204:207], v[220:223], v[18:33]
	v_mfma_f32_32x32x16_bf16 v[18:33], v[208:211], v[224:227], v[18:33]
	ds_read2_b64 v[204:207], v239 offset0:104 offset1:106
	ds_read2_b64 v[208:211], v239 offset0:108 offset1:110
	s_waitcnt lgkmcnt(2)
	v_mfma_f32_32x32x16_bf16 v[2:17], v[196:199], v[172:175], v[2:17]
	v_mfma_f32_32x32x16_bf16 v[2:17], v[200:203], v[176:179], v[2:17]
	s_waitcnt lgkmcnt(0)
	v_mfma_f32_32x32x16_bf16 v[2:17], v[204:207], v[220:223], v[2:17]
	v_mfma_f32_32x32x16_bf16 v[2:17], v[208:211], v[224:227], v[2:17]
.Lda_nopv:
	s_cmp_le_i32 s29, s24
	s_nop 1
	s_cbranch_scc1 .LBB0_193
	v_add_u32_e32 v0, s28, v194
	v_add_u32_e32 v162, 0x15a00, v0
	v_add_u32_e32 v164, 0x15a80, v0
	ds_read2_b32 v[162:163], v162 offset1:1
	ds_read2_b32 v[164:165], v164 offset1:1
	v_add_u32_e32 v166, 0x15a08, v0
	v_add_u32_e32 v168, 0x15a88, v0
	v_add_u32_e32 v170, 0x15a20, v0
	v_add_u32_e32 v172, 0x15aa0, v0
	v_add_u32_e32 v174, 0x15a28, v0
	v_add_u32_e32 v176, 0x15aa8, v0
	v_add_u32_e32 v178, 0x15a40, v0
	v_add_u32_e32 v195, 0x15ac0, v0
	ds_read2_b32 v[166:167], v166 offset1:1
	ds_read2_b32 v[168:169], v168 offset1:1
	ds_read2_b32 v[170:171], v170 offset1:1
	ds_read2_b32 v[172:173], v172 offset1:1
	ds_read2_b32 v[174:175], v174 offset1:1
	ds_read2_b32 v[176:177], v176 offset1:1
	ds_read2_b32 v[178:179], v178 offset1:1
	ds_read2_b32 v[196:197], v195 offset1:1
	v_add_u32_e32 v195, 0x15a48, v0
	v_add_u32_e32 v200, 0x15ac8, v0
	ds_read2_b32 v[198:199], v195 offset1:1
	ds_read2_b32 v[200:201], v200 offset1:1
	v_add_u32_e32 v195, 0x15a60, v0
	v_add_u32_e32 v204, 0x15ae0, v0
	ds_read2_b32 v[202:203], v195 offset1:1
	ds_read2_b32 v[204:205], v204 offset1:1
	v_add_u32_e32 v195, 0x15a68, v0
	v_add_u32_e32 v0, 0x15ae8, v0
	ds_read2_b32 v[208:209], v195 offset1:1
	s_waitcnt lgkmcnt(0)
	v_pk_add_f32 v[84:85], v[84:85], v[162:163]
	ds_read2_b32 v[162:163], v0 offset1:1
	v_pk_add_f32 v[96:97], v[96:97], v[202:203]
	v_pk_add_f32 v[94:95], v[94:95], v[198:199]
	v_pk_add_f32 v[98:99], v[98:99], v[208:209]
	v_pk_add_f32 v[92:93], v[92:93], v[178:179]
	v_pk_add_f32 v[90:91], v[90:91], v[174:175]
	v_pk_add_f32 v[88:89], v[88:89], v[170:171]
	v_pk_add_f32 v[86:87], v[86:87], v[166:167]
	s_waitcnt lgkmcnt(0)
	v_pk_add_f32 v[114:115], v[114:115], v[162:163]
	v_pk_add_f32 v[112:113], v[112:113], v[204:205]
	v_pk_add_f32 v[110:111], v[110:111], v[200:201]
	v_pk_add_f32 v[108:109], v[108:109], v[196:197]
	v_pk_add_f32 v[106:107], v[106:107], v[176:177]
	v_pk_add_f32 v[104:105], v[104:105], v[172:173]
	v_pk_add_f32 v[102:103], v[102:103], v[168:169]
	v_pk_add_f32 v[100:101], v[100:101], v[164:165]

; #define LAS __attribute__((address_space(3)))
; DI unsigned cvtpk(float lo, float hi) { f32x2_t v = {lo, hi}; bf16x2_t b = __builtin_convertvector(v, bf16x2_t); return __builtin_bit_cast(unsigned, b); }
; DI float ex2(float x) { return __builtin_amdgcn_exp2f(x); }
; template <int MODE>
; DI void attn_unit(LAS unsigned char* lds, const bf16_t* Qg, int ldq, const bf16_t* Kg, int ldk, const bf16_t* VTg, int ldvt, bf16_t* Og, int ldo,
;                   int q0, int NT, const float* gout, const float* relb, float lam, float osc, const float* qgain) {
;     ...
;                 for (int i = 0; i < 16; ++i) { p0[i] = ex2(p0[i]); p1[i] = ex2(p1[i]); rs += p0[i] + p1[i]; }
;                 lrun += rs;
;     ...
;             for (int j = 0; j < 4; ++j) { pk[0][j] = cvtpk(p0[2 * j], p0[2 * j + 1]); pk[1][j] = cvtpk(p0[8 + 2 * j], p0[8 + 2 * j + 1]);
;                 pk[2][j] = cvtpk(p1[2 * j], p1[2 * j + 1]); pk[3][j] = cvtpk(p1[8 + 2 * j], p1[8 + 2 * j + 1]); }
;             if (!skew) pvdo(vcur, pk);
;         }
;         if (MODE == 2 && SB_EARLY) { if (lane == 0) ((LAS unsigned*)(lds + FLG))[cur * 8 + wid] = (!active || __any(R > -150.f)) ? 1u : 0u; }
;         if (t + 1 < NT) AT_LSTORE(cur ^ 1, vnext);
.LBB0_197:
	v_add_f32_e32 v241, v179, v196
	v_add_f32_e32 v242, v0, v178
	v_add_f32_e32 v243, v175, v177
	v_add_f32_e32 v244, v174, v176
	v_add_f32_e32 v245, v171, v173
	v_add_f32_e32 v206, v170, v172
	v_add_f32_e32 v207, v167, v169
	v_add_f32_e32 v210, v166, v168
	v_add_f32_e32 v211, v163, v165
	v_add_f32_e32 v230, v162, v164
	v_add_f32_e32 v231, v109, v195
	v_add_f32_e32 v233, v108, v110
	v_add_f32_e32 v234, v105, v107
	v_add_f32_e32 v236, v104, v106
	v_add_f32_e32 v237, v101, v103
	v_add_f32_e32 v238, v100, v102
	v_add_f32_e32 v241, v241, v242
	v_add_f32_e32 v243, v243, v244
	v_add_f32_e32 v245, v245, v206
	v_add_f32_e32 v207, v207, v210
	v_add_f32_e32 v211, v211, v230
	v_add_f32_e32 v231, v231, v233
	v_add_f32_e32 v234, v234, v236
	v_add_f32_e32 v237, v237, v238
	v_add_f32_e32 v241, v241, v243
	v_add_f32_e32 v245, v245, v207
	v_add_f32_e32 v211, v211, v231
	v_add_f32_e32 v234, v234, v237
	v_add_f32_e32 v241, v241, v245
	v_add_f32_e32 v211, v211, v234
	v_add_f32_e32 v241, v241, v211
	v_add_f32_e32 v153, v153, v241
	s_and_b64 vcc, exec, s[0:1]
	s_cbranch_vccz .Lda_nosave
	v_mov_b64_e32 v[172:173], v[96:97]
	v_mov_b64_e32 v[174:175], v[98:99]
	v_mov_b64_e32 v[176:177], v[92:93]
	v_mov_b64_e32 v[178:179], v[94:95]
	v_mov_b64_e32 v[220:221], v[88:89]
	v_mov_b64_e32 v[222:223], v[90:91]
	v_mov_b64_e32 v[224:225], v[84:85]
	v_mov_b64_e32 v[226:227], v[86:87]
.Lda_nosave:
.LBB0_198:
	s_add_i32 s2, s13, 1
	s_cmp_lg_u32 s13, 2
	s_cselect_b32 s13, s2, 0
	s_andn2_b64 vcc, exec, s[8:9]
	s_cbranch_vccnz .LBB0_181
	s_cmp_eq_u32 s10, 0
	s_cselect_b32 s2, 0x4400, 0
	v_add3_u32 v0, s2, v192, v193
	s_waitcnt vmcnt(0) lgkmcnt(0)
	ds_write_b128 v0, v[132:135]

; #define LAS __attribute__((address_space(3)))
; #define MFMA32(a, b, c) __builtin_amdgcn_mfma_f32_32x32x16_bf16((a), (b), (c), 0, 0, 0)
; template <int MODE>
; DI void attn_unit(LAS unsigned char* lds, const bf16_t* Qg, int ldq, const bf16_t* Kg, int ldk, const bf16_t* VTg, int ldvt, bf16_t* Og, int ldo,
;                   int q0, int NT, const float* gout, const float* relb, float lam, float osc, const float* qgain) {
;     ...
;     auto pvdo = [&](const int vbi, const u32x4 (&pp)[4]) {
;         const LAS unsigned char* Vb = lds + VB0 + vbi * VBSZ + (r32 + (MODE == 2 ? mm * 64 : 0)) * VSTR + hi * 8;
; #pragma unroll
;         for (int d = 0; d < NDB; ++d)
; #pragma unroll
;             for (int ks = 0; ks < 4; ++ks) { const int kb = 32 * (ks >> 1) + 16 * (ks & 1);
;                 const s16x4 lo = *(const LAS s16x4*)(Vb + d * 32 * VSTR + kb * 2), hh = *(const LAS s16x4*)(Vb + d * 32 * VSTR + kb * 2 + 16);
;                 const bf16x8 vf = __builtin_shufflevector(lo, hh, 0, 1, 2, 3, 4, 5, 6, 7);
;                 o[d] = MFMA32(vf, __builtin_bit_cast(bf16x8, pp[ks]), o[d]); }
;     };
;     ...
;         if (skew && t >= 1 && (t - 1) < ntw) pvdo(vprev, pk);
.Lda_inactive:
	s_and_b32 s10, s2, 1
	s_cbranch_vccz .LBB0_198
	s_mul_i32 s3, s13, 0x4400
	s_addk_i32 s3, 0xbc00
	s_cmp_lg_u32 s13, 0
	s_cselect_b32 s3, s3, 0x8800
	v_add_u32_e32 v0, s3, v67
	v_add_u32_e32 v236, 0x8800, v0
	v_add_u32_e32 v237, 0x9800, v0
	v_add_u32_e32 v238, 0xa800, v0
	v_add_u32_e32 v239, 0xb800, v0
	ds_read2_b64 v[196:199], v236 offset1:2
	ds_read2_b64 v[200:203], v236 offset0:4 offset1:6
	ds_read2_b64 v[204:207], v236 offset0:8 offset1:10
	ds_read2_b64 v[208:211], v236 offset0:12 offset1:14
	s_waitcnt lgkmcnt(2)
	v_mfma_f32_32x32x16_bf16 v[50:65], v[196:199], v[172:175], v[50:65]
	v_mfma_f32_32x32x16_bf16 v[50:65], v[200:203], v[176:179], v[50:65]
	ds_read2_b64 v[196:199], v237 offset0:32 offset1:34
	ds_read2_b64 v[200:203], v237 offset0:36 offset1:38
	s_waitcnt lgkmcnt(2)
	v_mfma_f32_32x32x16_bf16 v[50:65], v[204:207], v[220:223], v[50:65]
	v_mfma_f32_32x32x16_bf16 v[50:65], v[208:211], v[224:227], v[50:65]
	ds_read2_b64 v[204:207], v237 offset0:40 offset1:42
	ds_read2_b64 v[208:211], v237 offset0:44 offset1:46
	s_waitcnt lgkmcnt(2)
	v_mfma_f32_32x32x16_bf16 v[34:49], v[196:199], v[172:175], v[34:49]
	v_mfma_f32_32x32x16_bf16 v[34:49], v[200:203], v[176:179], v[34:49]
	ds_read2_b64 v[196:199], v238 offset0:64 offset1:66
	ds_read2_b64 v[200:203], v238 offset0:68 offset1:70
	s_waitcnt lgkmcnt(2)
	v_mfma_f32_32x32x16_bf16 v[34:49], v[204:207], v[220:223], v[34:49]
	v_mfma_f32_32x32x16_bf16 v[34:49], v[208:211], v[224:227], v[34:49]
	ds_read2_b64 v[204:207], v238 offset0:72 offset1:74
	ds_read2_b64 v[208:211], v238 offset0:76 offset1:78
	s_waitcnt lgkmcnt(2)
	v_mfma_f32_32x32x16_bf16 v[18:33], v[196:199], v[172:175], v[18:33]
	v_mfma_f32_32x32x16_bf16 v[18:33], v[200:203], v[176:179], v[18:33]
	ds_read2_b64 v[196:199], v239 offset0:96 offset1:98
	ds_read2_b64 v[200:203], v239 offset0:100 offset1:102
	s_waitcnt lgkmcnt(2)
	v_mfma_f32_32x32x16_bf16 v[18:33], v[204:207], v[220:223], v[18:33]
	v_mfma_f32_32x32x16_bf16 v[18:33], v[208:211], v[224:227], v[18:33]
	ds_read2_b64 v[204:207], v239 offset0:104 offset1:106
	ds_read2_b64 v[208:211], v239 offset0:108 offset1:110
	s_waitcnt lgkmcnt(2)
	v_mfma_f32_32x32x16_bf16 v[2:17], v[196:199], v[172:175], v[2:17]
	v_mfma_f32_32x32x16_bf16 v[2:17], v[200:203], v[176:179], v[2:17]
	s_waitcnt lgkmcnt(0)
	v_mfma_f32_32x32x16_bf16 v[2:17], v[204:207], v[220:223], v[2:17]
	v_mfma_f32_32x32x16_bf16 v[2:17], v[208:211], v[224:227], v[2:17]
	s_branch .LBB0_198
